# adaLN partial sums in one pass: second chunk's loads issued as first chunk's registers free up
# baseline (speedup 1.0000x reference)
.LBB0_15:
	v_readfirstlane_b32 s8, v78
	v_readfirstlane_b32 s9, v79
	s_add_i32 s93, s91, s92
	s_add_i32 s10, s93, 0x20000
	v_mov_b32_e32 v1, s10
	s_sub_u32 s8, s8, 0xc0000
	s_subb_u32 s9, s9, 0
	s_nop 4
	global_load_dwordx2 v[6:7], v158, s[8:9] nt
	s_add_u32 s8, s8, 0x6000
	s_addc_u32 s9, s9, 0
	global_load_dwordx2 v[8:9], v158, s[8:9] nt
	s_add_u32 s8, s8, 0x6000
	s_addc_u32 s9, s9, 0
	global_load_dwordx2 v[10:11], v158, s[8:9] nt
	s_add_u32 s8, s8, 0x6000
	s_addc_u32 s9, s9, 0
	global_load_dwordx2 v[12:13], v158, s[8:9] nt
	s_add_u32 s8, s8, 0x6000
	s_addc_u32 s9, s9, 0
	global_load_dwordx2 v[14:15], v158, s[8:9] nt
	s_add_u32 s8, s8, 0x6000
	s_addc_u32 s9, s9, 0
	global_load_dwordx2 v[16:17], v158, s[8:9] nt
	s_add_u32 s8, s8, 0x6000
	s_addc_u32 s9, s9, 0
	global_load_dwordx2 v[18:19], v158, s[8:9] nt
	s_add_u32 s8, s8, 0x6000
	s_addc_u32 s9, s9, 0
	global_load_dwordx2 v[20:21], v158, s[8:9] nt
	s_add_u32 s8, s8, 0x6000
	s_addc_u32 s9, s9, 0
	global_load_dwordx2 v[22:23], v158, s[8:9] nt
	s_add_u32 s8, s8, 0x6000
	s_addc_u32 s9, s9, 0
	global_load_dwordx2 v[24:25], v158, s[8:9] nt
	s_add_u32 s8, s8, 0x6000
	s_addc_u32 s9, s9, 0
	global_load_dwordx2 v[26:27], v158, s[8:9] nt
	s_add_u32 s8, s8, 0x6000
	s_addc_u32 s9, s9, 0
	global_load_dwordx2 v[28:29], v158, s[8:9] nt
	s_add_u32 s8, s8, 0x6000
	s_addc_u32 s9, s9, 0
	global_load_dwordx2 v[30:31], v158, s[8:9] nt
	s_add_u32 s8, s8, 0x6000
	s_addc_u32 s9, s9, 0
	global_load_dwordx2 v[32:33], v158, s[8:9] nt
	s_add_u32 s8, s8, 0x6000
	s_addc_u32 s9, s9, 0
	global_load_dwordx2 v[34:35], v158, s[8:9] nt
	s_add_u32 s8, s8, 0x6000
	s_addc_u32 s9, s9, 0
	global_load_dwordx2 v[36:37], v158, s[8:9] nt
	s_add_u32 s8, s8, 0x6000
	s_addc_u32 s9, s9, 0
	global_load_dwordx2 v[38:39], v158, s[8:9] nt
	s_add_u32 s8, s8, 0x6000
	s_addc_u32 s9, s9, 0
	global_load_dwordx2 v[40:41], v158, s[8:9] nt
	s_add_u32 s8, s8, 0x6000
	s_addc_u32 s9, s9, 0
	global_load_dwordx2 v[42:43], v158, s[8:9] nt
	s_add_u32 s8, s8, 0x6000
	s_addc_u32 s9, s9, 0
	global_load_dwordx2 v[44:45], v158, s[8:9] nt
	s_add_u32 s8, s8, 0x6000
	s_addc_u32 s9, s9, 0
	global_load_dwordx2 v[46:47], v158, s[8:9] nt
	s_add_u32 s8, s8, 0x6000
	s_addc_u32 s9, s9, 0
	global_load_dwordx2 v[48:49], v158, s[8:9] nt
	s_add_u32 s8, s8, 0x6000
	s_addc_u32 s9, s9, 0
	global_load_dwordx2 v[50:51], v158, s[8:9] nt
	s_add_u32 s8, s8, 0x6000
	s_addc_u32 s9, s9, 0
	global_load_dwordx2 v[52:53], v158, s[8:9] nt
	s_add_u32 s8, s8, 0x6000
	s_addc_u32 s9, s9, 0
	global_load_dwordx2 v[54:55], v158, s[8:9] nt
	s_add_u32 s8, s8, 0x6000
	s_addc_u32 s9, s9, 0
	global_load_dwordx2 v[56:57], v158, s[8:9] nt
	s_add_u32 s8, s8, 0x6000
	s_addc_u32 s9, s9, 0
	global_load_dwordx2 v[58:59], v158, s[8:9] nt
	s_add_u32 s8, s8, 0x6000
	s_addc_u32 s9, s9, 0
	global_load_dwordx2 v[60:61], v158, s[8:9] nt
	s_add_u32 s8, s8, 0x6000
	s_addc_u32 s9, s9, 0
	global_load_dwordx2 v[62:63], v158, s[8:9] nt
	s_add_u32 s8, s8, 0x6000
	s_addc_u32 s9, s9, 0
	global_load_dwordx2 v[64:65], v158, s[8:9] nt
	s_add_u32 s8, s8, 0x6000
	s_addc_u32 s9, s9, 0
	global_load_dwordx2 v[66:67], v158, s[8:9] nt
	s_add_u32 s8, s8, 0x6000
	s_addc_u32 s9, s9, 0
	global_load_dwordx2 v[68:69], v158, s[8:9] nt
	s_add_u32 s8, s8, 0x6000
	s_addc_u32 s9, s9, 0
	global_load_dwordx2 v[70:71], v158, s[8:9] nt
	s_add_u32 s8, s8, 0x6000
	s_addc_u32 s9, s9, 0
	global_load_dwordx2 v[72:73], v158, s[8:9] nt
	s_add_u32 s8, s8, 0x6000
	s_addc_u32 s9, s9, 0
	global_load_dwordx2 v[80:81], v158, s[8:9] nt
	s_add_u32 s8, s8, 0x6000
	s_addc_u32 s9, s9, 0
	global_load_dwordx2 v[82:83], v158, s[8:9] nt
	s_add_u32 s8, s8, 0x6000
	s_addc_u32 s9, s9, 0
	global_load_dwordx2 v[84:85], v158, s[8:9] nt
	s_add_u32 s8, s8, 0x6000
	s_addc_u32 s9, s9, 0
	global_load_dwordx2 v[86:87], v158, s[8:9] nt
	s_add_u32 s8, s8, 0x6000
	s_addc_u32 s9, s9, 0
	global_load_dwordx2 v[88:89], v158, s[8:9] nt
	s_add_u32 s8, s8, 0x6000
	s_addc_u32 s9, s9, 0
	global_load_dwordx2 v[90:91], v158, s[8:9] nt
	s_add_u32 s8, s8, 0x6000
	s_addc_u32 s9, s9, 0
	global_load_dwordx2 v[92:93], v158, s[8:9] nt
	s_add_u32 s8, s8, 0x6000
	s_addc_u32 s9, s9, 0
	global_load_dwordx2 v[94:95], v158, s[8:9] nt
	s_add_u32 s8, s8, 0x6000
	s_addc_u32 s9, s9, 0
	global_load_dwordx2 v[96:97], v158, s[8:9] nt
	s_add_u32 s8, s8, 0x6000
	s_addc_u32 s9, s9, 0
	global_load_dwordx2 v[98:99], v158, s[8:9] nt
	s_add_u32 s8, s8, 0x6000
	s_addc_u32 s9, s9, 0
	global_load_dwordx2 v[100:101], v158, s[8:9] nt
	s_add_u32 s8, s8, 0x6000
	s_addc_u32 s9, s9, 0
	global_load_dwordx2 v[102:103], v158, s[8:9] nt
	s_add_u32 s8, s8, 0x6000
	s_addc_u32 s9, s9, 0
	global_load_dwordx2 v[104:105], v158, s[8:9] nt
	s_add_u32 s8, s8, 0x6000
	s_addc_u32 s9, s9, 0
	global_load_dwordx2 v[106:107], v158, s[8:9] nt
	s_add_u32 s8, s8, 0x6000
	s_addc_u32 s9, s9, 0
	global_load_dwordx2 v[108:109], v158, s[8:9] nt
	s_add_u32 s8, s8, 0x6000
	s_addc_u32 s9, s9, 0
	global_load_dwordx2 v[110:111], v158, s[8:9] nt
	s_add_u32 s8, s8, 0x6000
	s_addc_u32 s9, s9, 0
	global_load_dwordx2 v[112:113], v158, s[8:9] nt
	s_add_u32 s8, s8, 0x6000
	s_addc_u32 s9, s9, 0
	global_load_dwordx2 v[114:115], v158, s[8:9] nt
	s_add_u32 s8, s8, 0x6000
	s_addc_u32 s9, s9, 0
	global_load_dwordx2 v[116:117], v158, s[8:9] nt
	s_add_u32 s8, s8, 0x6000
	s_addc_u32 s9, s9, 0
	global_load_dwordx2 v[118:119], v158, s[8:9] nt
	s_add_u32 s8, s8, 0x6000
	s_addc_u32 s9, s9, 0
	global_load_dwordx2 v[120:121], v158, s[8:9] nt
	s_add_u32 s8, s8, 0x6000
	s_addc_u32 s9, s9, 0
	global_load_dwordx2 v[122:123], v158, s[8:9] nt
	s_add_u32 s8, s8, 0x6000
	s_addc_u32 s9, s9, 0
	global_load_dwordx2 v[124:125], v158, s[8:9] nt
	s_add_u32 s8, s8, 0x6000
	s_addc_u32 s9, s9, 0
	global_load_dwordx2 v[126:127], v158, s[8:9] nt
	s_add_u32 s8, s8, 0x6000
	s_addc_u32 s9, s9, 0
	global_load_dwordx2 v[128:129], v158, s[8:9] nt
	s_add_u32 s8, s8, 0x6000
	s_addc_u32 s9, s9, 0
	global_load_dwordx2 v[130:131], v158, s[8:9] nt
	s_add_u32 s8, s8, 0x6000
	s_addc_u32 s9, s9, 0
	global_load_dwordx2 v[132:133], v158, s[8:9] nt
	s_add_u32 s8, s8, 0x6000
	s_addc_u32 s9, s9, 0
	global_load_dwordx2 v[134:135], v158, s[8:9] nt
	s_add_u32 s8, s8, 0x6000
	s_addc_u32 s9, s9, 0
	global_load_dwordx2 v[136:137], v158, s[8:9] nt
	s_add_u32 s8, s8, 0x6000
	s_addc_u32 s9, s9, 0
	global_load_dwordx2 v[138:139], v158, s[8:9] nt
	s_add_u32 s8, s8, 0x6000
	s_addc_u32 s9, s9, 0
	ds_read_b128 v[140:143], v1
	ds_read_b128 v[144:147], v1 offset:4096
	ds_read_b128 v[148:151], v1 offset:16
	ds_read_b128 v[152:155], v1 offset:4112
	s_waitcnt vmcnt(60) lgkmcnt(2)
	v_pk_fma_f32 v[4:5], v[6:7], v[140:141], v[4:5] op_sel_hi:[1,0,1]
	v_pk_fma_f32 v[2:3], v[6:7], v[144:145], v[2:3] op_sel_hi:[1,0,1]
	v_pk_fma_f32 v[4:5], v[8:9], v[140:141], v[4:5] op_sel:[0,1,0]
	v_pk_fma_f32 v[2:3], v[8:9], v[144:145], v[2:3] op_sel:[0,1,0]
	v_pk_fma_f32 v[4:5], v[10:11], v[142:143], v[4:5] op_sel_hi:[1,0,1]
	v_pk_fma_f32 v[2:3], v[10:11], v[146:147], v[2:3] op_sel_hi:[1,0,1]
	v_pk_fma_f32 v[4:5], v[12:13], v[142:143], v[4:5] op_sel:[0,1,0]
	v_pk_fma_f32 v[2:3], v[12:13], v[146:147], v[2:3] op_sel:[0,1,0]
	global_load_dwordx2 v[6:7], v158, s[8:9] nt
	s_add_u32 s8, s8, 0x6000
	s_addc_u32 s9, s9, 0
	global_load_dwordx2 v[8:9], v158, s[8:9] nt
	s_add_u32 s8, s8, 0x6000
	s_addc_u32 s9, s9, 0
	global_load_dwordx2 v[10:11], v158, s[8:9] nt
	s_add_u32 s8, s8, 0x6000
	s_addc_u32 s9, s9, 0
	global_load_dwordx2 v[12:13], v158, s[8:9] nt
	s_add_u32 s8, s8, 0x6000
	s_addc_u32 s9, s9, 0
	ds_read_b128 v[140:143], v1 offset:32
	ds_read_b128 v[144:147], v1 offset:4128
	s_waitcnt vmcnt(60) lgkmcnt(2)
	v_pk_fma_f32 v[4:5], v[14:15], v[148:149], v[4:5] op_sel_hi:[1,0,1]
	v_pk_fma_f32 v[2:3], v[14:15], v[152:153], v[2:3] op_sel_hi:[1,0,1]
	v_pk_fma_f32 v[4:5], v[16:17], v[148:149], v[4:5] op_sel:[0,1,0]
	v_pk_fma_f32 v[2:3], v[16:17], v[152:153], v[2:3] op_sel:[0,1,0]
	v_pk_fma_f32 v[4:5], v[18:19], v[150:151], v[4:5] op_sel_hi:[1,0,1]
	v_pk_fma_f32 v[2:3], v[18:19], v[154:155], v[2:3] op_sel_hi:[1,0,1]
	v_pk_fma_f32 v[4:5], v[20:21], v[150:151], v[4:5] op_sel:[0,1,0]
	v_pk_fma_f32 v[2:3], v[20:21], v[154:155], v[2:3] op_sel:[0,1,0]
	global_load_dwordx2 v[14:15], v158, s[8:9] nt
	s_add_u32 s8, s8, 0x6000
	s_addc_u32 s9, s9, 0
	global_load_dwordx2 v[16:17], v158, s[8:9] nt
	s_add_u32 s8, s8, 0x6000
	s_addc_u32 s9, s9, 0
	global_load_dwordx2 v[18:19], v158, s[8:9] nt
	s_add_u32 s8, s8, 0x6000
	s_addc_u32 s9, s9, 0
	global_load_dwordx2 v[20:21], v158, s[8:9] nt
	s_add_u32 s8, s8, 0x6000
	s_addc_u32 s9, s9, 0
	ds_read_b128 v[148:151], v1 offset:48
	ds_read_b128 v[152:155], v1 offset:4144
	s_waitcnt vmcnt(60) lgkmcnt(2)
	v_pk_fma_f32 v[4:5], v[22:23], v[140:141], v[4:5] op_sel_hi:[1,0,1]
	v_pk_fma_f32 v[2:3], v[22:23], v[144:145], v[2:3] op_sel_hi:[1,0,1]
	v_pk_fma_f32 v[4:5], v[24:25], v[140:141], v[4:5] op_sel:[0,1,0]
	v_pk_fma_f32 v[2:3], v[24:25], v[144:145], v[2:3] op_sel:[0,1,0]
	v_pk_fma_f32 v[4:5], v[26:27], v[142:143], v[4:5] op_sel_hi:[1,0,1]
	v_pk_fma_f32 v[2:3], v[26:27], v[146:147], v[2:3] op_sel_hi:[1,0,1]
	v_pk_fma_f32 v[4:5], v[28:29], v[142:143], v[4:5] op_sel:[0,1,0]
	v_pk_fma_f32 v[2:3], v[28:29], v[146:147], v[2:3] op_sel:[0,1,0]
	global_load_dwordx2 v[22:23], v158, s[8:9] nt
	s_add_u32 s8, s8, 0x6000
	s_addc_u32 s9, s9, 0
	global_load_dwordx2 v[24:25], v158, s[8:9] nt
	s_add_u32 s8, s8, 0x6000
	s_addc_u32 s9, s9, 0
	global_load_dwordx2 v[26:27], v158, s[8:9] nt
	s_add_u32 s8, s8, 0x6000
	s_addc_u32 s9, s9, 0
	global_load_dwordx2 v[28:29], v158, s[8:9] nt
	s_add_u32 s8, s8, 0x6000
	s_addc_u32 s9, s9, 0
	ds_read_b128 v[140:143], v1 offset:64
	ds_read_b128 v[144:147], v1 offset:4160
	s_waitcnt vmcnt(60) lgkmcnt(2)
	v_pk_fma_f32 v[4:5], v[30:31], v[148:149], v[4:5] op_sel_hi:[1,0,1]
	v_pk_fma_f32 v[2:3], v[30:31], v[152:153], v[2:3] op_sel_hi:[1,0,1]
	v_pk_fma_f32 v[4:5], v[32:33], v[148:149], v[4:5] op_sel:[0,1,0]
	v_pk_fma_f32 v[2:3], v[32:33], v[152:153], v[2:3] op_sel:[0,1,0]
	v_pk_fma_f32 v[4:5], v[34:35], v[150:151], v[4:5] op_sel_hi:[1,0,1]
	v_pk_fma_f32 v[2:3], v[34:35], v[154:155], v[2:3] op_sel_hi:[1,0,1]
	v_pk_fma_f32 v[4:5], v[36:37], v[150:151], v[4:5] op_sel:[0,1,0]
	v_pk_fma_f32 v[2:3], v[36:37], v[154:155], v[2:3] op_sel:[0,1,0]
	global_load_dwordx2 v[30:31], v158, s[8:9] nt
	s_add_u32 s8, s8, 0x6000
	s_addc_u32 s9, s9, 0
	global_load_dwordx2 v[32:33], v158, s[8:9] nt
	s_add_u32 s8, s8, 0x6000
	s_addc_u32 s9, s9, 0
	global_load_dwordx2 v[34:35], v158, s[8:9] nt
	s_add_u32 s8, s8, 0x6000
	s_addc_u32 s9, s9, 0
	global_load_dwordx2 v[36:37], v158, s[8:9] nt
	s_add_u32 s8, s8, 0x6000
	s_addc_u32 s9, s9, 0
	ds_read_b128 v[148:151], v1 offset:80
	ds_read_b128 v[152:155], v1 offset:4176
	s_waitcnt vmcnt(60) lgkmcnt(2)
	v_pk_fma_f32 v[4:5], v[38:39], v[140:141], v[4:5] op_sel_hi:[1,0,1]
	v_pk_fma_f32 v[2:3], v[38:39], v[144:145], v[2:3] op_sel_hi:[1,0,1]
	v_pk_fma_f32 v[4:5], v[40:41], v[140:141], v[4:5] op_sel:[0,1,0]
	v_pk_fma_f32 v[2:3], v[40:41], v[144:145], v[2:3] op_sel:[0,1,0]
	v_pk_fma_f32 v[4:5], v[42:43], v[142:143], v[4:5] op_sel_hi:[1,0,1]
	v_pk_fma_f32 v[2:3], v[42:43], v[146:147], v[2:3] op_sel_hi:[1,0,1]
	v_pk_fma_f32 v[4:5], v[44:45], v[142:143], v[4:5] op_sel:[0,1,0]
	v_pk_fma_f32 v[2:3], v[44:45], v[146:147], v[2:3] op_sel:[0,1,0]
	global_load_dwordx2 v[38:39], v158, s[8:9] nt
	s_add_u32 s8, s8, 0x6000
	s_addc_u32 s9, s9, 0
	global_load_dwordx2 v[40:41], v158, s[8:9] nt
	s_add_u32 s8, s8, 0x6000
	s_addc_u32 s9, s9, 0
	global_load_dwordx2 v[42:43], v158, s[8:9] nt
	s_add_u32 s8, s8, 0x6000
	s_addc_u32 s9, s9, 0
	global_load_dwordx2 v[44:45], v158, s[8:9] nt
	s_add_u32 s8, s8, 0x6000
	s_addc_u32 s9, s9, 0
	ds_read_b128 v[140:143], v1 offset:96
	ds_read_b128 v[144:147], v1 offset:4192
	s_waitcnt vmcnt(60) lgkmcnt(2)
	v_pk_fma_f32 v[4:5], v[46:47], v[148:149], v[4:5] op_sel_hi:[1,0,1]
	v_pk_fma_f32 v[2:3], v[46:47], v[152:153], v[2:3] op_sel_hi:[1,0,1]
	v_pk_fma_f32 v[4:5], v[48:49], v[148:149], v[4:5] op_sel:[0,1,0]
	v_pk_fma_f32 v[2:3], v[48:49], v[152:153], v[2:3] op_sel:[0,1,0]
	v_pk_fma_f32 v[4:5], v[50:51], v[150:151], v[4:5] op_sel_hi:[1,0,1]
	v_pk_fma_f32 v[2:3], v[50:51], v[154:155], v[2:3] op_sel_hi:[1,0,1]
	v_pk_fma_f32 v[4:5], v[52:53], v[150:151], v[4:5] op_sel:[0,1,0]
	v_pk_fma_f32 v[2:3], v[52:53], v[154:155], v[2:3] op_sel:[0,1,0]
	global_load_dwordx2 v[46:47], v158, s[8:9] nt
	s_add_u32 s8, s8, 0x6000
	s_addc_u32 s9, s9, 0
	global_load_dwordx2 v[48:49], v158, s[8:9] nt
	s_add_u32 s8, s8, 0x6000
	s_addc_u32 s9, s9, 0
	global_load_dwordx2 v[50:51], v158, s[8:9] nt
	s_add_u32 s8, s8, 0x6000
	s_addc_u32 s9, s9, 0
	global_load_dwordx2 v[52:53], v158, s[8:9] nt
	s_add_u32 s8, s8, 0x6000
	s_addc_u32 s9, s9, 0
	ds_read_b128 v[148:151], v1 offset:112
	ds_read_b128 v[152:155], v1 offset:4208
	s_waitcnt vmcnt(60) lgkmcnt(2)
	v_pk_fma_f32 v[4:5], v[54:55], v[140:141], v[4:5] op_sel_hi:[1,0,1]
	v_pk_fma_f32 v[2:3], v[54:55], v[144:145], v[2:3] op_sel_hi:[1,0,1]
	v_pk_fma_f32 v[4:5], v[56:57], v[140:141], v[4:5] op_sel:[0,1,0]
	v_pk_fma_f32 v[2:3], v[56:57], v[144:145], v[2:3] op_sel:[0,1,0]
	v_pk_fma_f32 v[4:5], v[58:59], v[142:143], v[4:5] op_sel_hi:[1,0,1]
	v_pk_fma_f32 v[2:3], v[58:59], v[146:147], v[2:3] op_sel_hi:[1,0,1]
	v_pk_fma_f32 v[4:5], v[60:61], v[142:143], v[4:5] op_sel:[0,1,0]
	v_pk_fma_f32 v[2:3], v[60:61], v[146:147], v[2:3] op_sel:[0,1,0]
	global_load_dwordx2 v[54:55], v158, s[8:9] nt
	s_add_u32 s8, s8, 0x6000
	s_addc_u32 s9, s9, 0
	global_load_dwordx2 v[56:57], v158, s[8:9] nt
	s_add_u32 s8, s8, 0x6000
	s_addc_u32 s9, s9, 0
	global_load_dwordx2 v[58:59], v158, s[8:9] nt
	s_add_u32 s8, s8, 0x6000
	s_addc_u32 s9, s9, 0
	global_load_dwordx2 v[60:61], v158, s[8:9] nt
	s_add_u32 s8, s8, 0x6000
	s_addc_u32 s9, s9, 0
	ds_read_b128 v[140:143], v1 offset:128
	ds_read_b128 v[144:147], v1 offset:4224
	s_waitcnt vmcnt(60) lgkmcnt(2)
	v_pk_fma_f32 v[4:5], v[62:63], v[148:149], v[4:5] op_sel_hi:[1,0,1]
	v_pk_fma_f32 v[2:3], v[62:63], v[152:153], v[2:3] op_sel_hi:[1,0,1]
	v_pk_fma_f32 v[4:5], v[64:65], v[148:149], v[4:5] op_sel:[0,1,0]
	v_pk_fma_f32 v[2:3], v[64:65], v[152:153], v[2:3] op_sel:[0,1,0]
	v_pk_fma_f32 v[4:5], v[66:67], v[150:151], v[4:5] op_sel_hi:[1,0,1]
	v_pk_fma_f32 v[2:3], v[66:67], v[154:155], v[2:3] op_sel_hi:[1,0,1]
	v_pk_fma_f32 v[4:5], v[68:69], v[150:151], v[4:5] op_sel:[0,1,0]
	v_pk_fma_f32 v[2:3], v[68:69], v[154:155], v[2:3] op_sel:[0,1,0]
	global_load_dwordx2 v[62:63], v158, s[8:9] nt
	s_add_u32 s8, s8, 0x6000
	s_addc_u32 s9, s9, 0
	global_load_dwordx2 v[64:65], v158, s[8:9] nt
	s_add_u32 s8, s8, 0x6000
	s_addc_u32 s9, s9, 0
	global_load_dwordx2 v[66:67], v158, s[8:9] nt
	s_add_u32 s8, s8, 0x6000
	s_addc_u32 s9, s9, 0
	global_load_dwordx2 v[68:69], v158, s[8:9] nt
	s_add_u32 s8, s8, 0x6000
	s_addc_u32 s9, s9, 0
	ds_read_b128 v[148:151], v1 offset:144
	ds_read_b128 v[152:155], v1 offset:4240
	s_waitcnt vmcnt(60) lgkmcnt(2)
	v_pk_fma_f32 v[4:5], v[70:71], v[140:141], v[4:5] op_sel_hi:[1,0,1]
	v_pk_fma_f32 v[2:3], v[70:71], v[144:145], v[2:3] op_sel_hi:[1,0,1]
	v_pk_fma_f32 v[4:5], v[72:73], v[140:141], v[4:5] op_sel:[0,1,0]
	v_pk_fma_f32 v[2:3], v[72:73], v[144:145], v[2:3] op_sel:[0,1,0]
	v_pk_fma_f32 v[4:5], v[80:81], v[142:143], v[4:5] op_sel_hi:[1,0,1]
	v_pk_fma_f32 v[2:3], v[80:81], v[146:147], v[2:3] op_sel_hi:[1,0,1]
	v_pk_fma_f32 v[4:5], v[82:83], v[142:143], v[4:5] op_sel:[0,1,0]
	v_pk_fma_f32 v[2:3], v[82:83], v[146:147], v[2:3] op_sel:[0,1,0]
	global_load_dwordx2 v[70:71], v158, s[8:9] nt
	s_add_u32 s8, s8, 0x6000
	s_addc_u32 s9, s9, 0
	global_load_dwordx2 v[72:73], v158, s[8:9] nt
	s_add_u32 s8, s8, 0x6000
	s_addc_u32 s9, s9, 0
	global_load_dwordx2 v[80:81], v158, s[8:9] nt
	s_add_u32 s8, s8, 0x6000
	s_addc_u32 s9, s9, 0
	global_load_dwordx2 v[82:83], v158, s[8:9] nt
	s_add_u32 s8, s8, 0x6000
	s_addc_u32 s9, s9, 0
	ds_read_b128 v[140:143], v1 offset:160
	ds_read_b128 v[144:147], v1 offset:4256
	s_waitcnt vmcnt(60) lgkmcnt(2)
	v_pk_fma_f32 v[4:5], v[84:85], v[148:149], v[4:5] op_sel_hi:[1,0,1]
	v_pk_fma_f32 v[2:3], v[84:85], v[152:153], v[2:3] op_sel_hi:[1,0,1]
	v_pk_fma_f32 v[4:5], v[86:87], v[148:149], v[4:5] op_sel:[0,1,0]
	v_pk_fma_f32 v[2:3], v[86:87], v[152:153], v[2:3] op_sel:[0,1,0]
	v_pk_fma_f32 v[4:5], v[88:89], v[150:151], v[4:5] op_sel_hi:[1,0,1]
	v_pk_fma_f32 v[2:3], v[88:89], v[154:155], v[2:3] op_sel_hi:[1,0,1]
	v_pk_fma_f32 v[4:5], v[90:91], v[150:151], v[4:5] op_sel:[0,1,0]
	v_pk_fma_f32 v[2:3], v[90:91], v[154:155], v[2:3] op_sel:[0,1,0]
	global_load_dwordx2 v[84:85], v158, s[8:9] nt
	s_add_u32 s8, s8, 0x6000
	s_addc_u32 s9, s9, 0
	global_load_dwordx2 v[86:87], v158, s[8:9] nt
	s_add_u32 s8, s8, 0x6000
	s_addc_u32 s9, s9, 0
	global_load_dwordx2 v[88:89], v158, s[8:9] nt
	s_add_u32 s8, s8, 0x6000
	s_addc_u32 s9, s9, 0
	global_load_dwordx2 v[90:91], v158, s[8:9] nt
	s_add_u32 s8, s8, 0x6000
	s_addc_u32 s9, s9, 0
	ds_read_b128 v[148:151], v1 offset:176
	ds_read_b128 v[152:155], v1 offset:4272
	s_waitcnt vmcnt(60) lgkmcnt(2)
	v_pk_fma_f32 v[4:5], v[92:93], v[140:141], v[4:5] op_sel_hi:[1,0,1]
	v_pk_fma_f32 v[2:3], v[92:93], v[144:145], v[2:3] op_sel_hi:[1,0,1]
	v_pk_fma_f32 v[4:5], v[94:95], v[140:141], v[4:5] op_sel:[0,1,0]
	v_pk_fma_f32 v[2:3], v[94:95], v[144:145], v[2:3] op_sel:[0,1,0]
	v_pk_fma_f32 v[4:5], v[96:97], v[142:143], v[4:5] op_sel_hi:[1,0,1]
	v_pk_fma_f32 v[2:3], v[96:97], v[146:147], v[2:3] op_sel_hi:[1,0,1]
	v_pk_fma_f32 v[4:5], v[98:99], v[142:143], v[4:5] op_sel:[0,1,0]
	v_pk_fma_f32 v[2:3], v[98:99], v[146:147], v[2:3] op_sel:[0,1,0]
	global_load_dwordx2 v[92:93], v158, s[8:9] nt
	s_add_u32 s8, s8, 0x6000
	s_addc_u32 s9, s9, 0
	global_load_dwordx2 v[94:95], v158, s[8:9] nt
	s_add_u32 s8, s8, 0x6000
	s_addc_u32 s9, s9, 0
	global_load_dwordx2 v[96:97], v158, s[8:9] nt
	s_add_u32 s8, s8, 0x6000
	s_addc_u32 s9, s9, 0
	global_load_dwordx2 v[98:99], v158, s[8:9] nt
	s_add_u32 s8, s8, 0x6000
	s_addc_u32 s9, s9, 0
	ds_read_b128 v[140:143], v1 offset:192
	ds_read_b128 v[144:147], v1 offset:4288
	s_waitcnt vmcnt(60) lgkmcnt(2)
	v_pk_fma_f32 v[4:5], v[100:101], v[148:149], v[4:5] op_sel_hi:[1,0,1]
	v_pk_fma_f32 v[2:3], v[100:101], v[152:153], v[2:3] op_sel_hi:[1,0,1]
	v_pk_fma_f32 v[4:5], v[102:103], v[148:149], v[4:5] op_sel:[0,1,0]
	v_pk_fma_f32 v[2:3], v[102:103], v[152:153], v[2:3] op_sel:[0,1,0]
	v_pk_fma_f32 v[4:5], v[104:105], v[150:151], v[4:5] op_sel_hi:[1,0,1]
	v_pk_fma_f32 v[2:3], v[104:105], v[154:155], v[2:3] op_sel_hi:[1,0,1]
	v_pk_fma_f32 v[4:5], v[106:107], v[150:151], v[4:5] op_sel:[0,1,0]
	v_pk_fma_f32 v[2:3], v[106:107], v[154:155], v[2:3] op_sel:[0,1,0]
	global_load_dwordx2 v[100:101], v158, s[8:9] nt
	s_add_u32 s8, s8, 0x6000
	s_addc_u32 s9, s9, 0
	global_load_dwordx2 v[102:103], v158, s[8:9] nt
	s_add_u32 s8, s8, 0x6000
	s_addc_u32 s9, s9, 0
	global_load_dwordx2 v[104:105], v158, s[8:9] nt
	s_add_u32 s8, s8, 0x6000
	s_addc_u32 s9, s9, 0
	global_load_dwordx2 v[106:107], v158, s[8:9] nt
	s_add_u32 s8, s8, 0x6000
	s_addc_u32 s9, s9, 0
	ds_read_b128 v[148:151], v1 offset:208
	ds_read_b128 v[152:155], v1 offset:4304
	s_waitcnt vmcnt(60) lgkmcnt(2)
	v_pk_fma_f32 v[4:5], v[108:109], v[140:141], v[4:5] op_sel_hi:[1,0,1]
	v_pk_fma_f32 v[2:3], v[108:109], v[144:145], v[2:3] op_sel_hi:[1,0,1]
	v_pk_fma_f32 v[4:5], v[110:111], v[140:141], v[4:5] op_sel:[0,1,0]
	v_pk_fma_f32 v[2:3], v[110:111], v[144:145], v[2:3] op_sel:[0,1,0]
	v_pk_fma_f32 v[4:5], v[112:113], v[142:143], v[4:5] op_sel_hi:[1,0,1]
	v_pk_fma_f32 v[2:3], v[112:113], v[146:147], v[2:3] op_sel_hi:[1,0,1]
	v_pk_fma_f32 v[4:5], v[114:115], v[142:143], v[4:5] op_sel:[0,1,0]
	v_pk_fma_f32 v[2:3], v[114:115], v[146:147], v[2:3] op_sel:[0,1,0]
	global_load_dwordx2 v[108:109], v158, s[8:9] nt
	s_add_u32 s8, s8, 0x6000
	s_addc_u32 s9, s9, 0
	global_load_dwordx2 v[110:111], v158, s[8:9] nt
	s_add_u32 s8, s8, 0x6000
	s_addc_u32 s9, s9, 0
	global_load_dwordx2 v[112:113], v158, s[8:9] nt
	s_add_u32 s8, s8, 0x6000
	s_addc_u32 s9, s9, 0
	global_load_dwordx2 v[114:115], v158, s[8:9] nt
	s_add_u32 s8, s8, 0x6000
	s_addc_u32 s9, s9, 0
	ds_read_b128 v[140:143], v1 offset:224
	ds_read_b128 v[144:147], v1 offset:4320
	s_waitcnt vmcnt(60) lgkmcnt(2)
	v_pk_fma_f32 v[4:5], v[116:117], v[148:149], v[4:5] op_sel_hi:[1,0,1]
	v_pk_fma_f32 v[2:3], v[116:117], v[152:153], v[2:3] op_sel_hi:[1,0,1]
	v_pk_fma_f32 v[4:5], v[118:119], v[148:149], v[4:5] op_sel:[0,1,0]
	v_pk_fma_f32 v[2:3], v[118:119], v[152:153], v[2:3] op_sel:[0,1,0]
	v_pk_fma_f32 v[4:5], v[120:121], v[150:151], v[4:5] op_sel_hi:[1,0,1]
	v_pk_fma_f32 v[2:3], v[120:121], v[154:155], v[2:3] op_sel_hi:[1,0,1]
	v_pk_fma_f32 v[4:5], v[122:123], v[150:151], v[4:5] op_sel:[0,1,0]
	v_pk_fma_f32 v[2:3], v[122:123], v[154:155], v[2:3] op_sel:[0,1,0]
	global_load_dwordx2 v[116:117], v158, s[8:9] nt
	s_add_u32 s8, s8, 0x6000
	s_addc_u32 s9, s9, 0
	global_load_dwordx2 v[118:119], v158, s[8:9] nt
	s_add_u32 s8, s8, 0x6000
	s_addc_u32 s9, s9, 0
	global_load_dwordx2 v[120:121], v158, s[8:9] nt
	s_add_u32 s8, s8, 0x6000
	s_addc_u32 s9, s9, 0
	global_load_dwordx2 v[122:123], v158, s[8:9] nt
	s_add_u32 s8, s8, 0x6000
	s_addc_u32 s9, s9, 0
	ds_read_b128 v[148:151], v1 offset:240
	ds_read_b128 v[152:155], v1 offset:4336
	s_waitcnt vmcnt(60) lgkmcnt(2)
	v_pk_fma_f32 v[4:5], v[124:125], v[140:141], v[4:5] op_sel_hi:[1,0,1]
	v_pk_fma_f32 v[2:3], v[124:125], v[144:145], v[2:3] op_sel_hi:[1,0,1]
	v_pk_fma_f32 v[4:5], v[126:127], v[140:141], v[4:5] op_sel:[0,1,0]
	v_pk_fma_f32 v[2:3], v[126:127], v[144:145], v[2:3] op_sel:[0,1,0]
	v_pk_fma_f32 v[4:5], v[128:129], v[142:143], v[4:5] op_sel_hi:[1,0,1]
	v_pk_fma_f32 v[2:3], v[128:129], v[146:147], v[2:3] op_sel_hi:[1,0,1]
	v_pk_fma_f32 v[4:5], v[130:131], v[142:143], v[4:5] op_sel:[0,1,0]
	v_pk_fma_f32 v[2:3], v[130:131], v[146:147], v[2:3] op_sel:[0,1,0]
	global_load_dwordx2 v[124:125], v158, s[8:9] nt
	s_add_u32 s8, s8, 0x6000
	s_addc_u32 s9, s9, 0
	global_load_dwordx2 v[126:127], v158, s[8:9] nt
	s_add_u32 s8, s8, 0x6000
	s_addc_u32 s9, s9, 0
	global_load_dwordx2 v[128:129], v158, s[8:9] nt
	s_add_u32 s8, s8, 0x6000
	s_addc_u32 s9, s9, 0
	global_load_dwordx2 v[130:131], v158, s[8:9] nt
	s_add_u32 s8, s8, 0x6000
	s_addc_u32 s9, s9, 0
	ds_read_b128 v[140:143], v1 offset:256
	ds_read_b128 v[144:147], v1 offset:4352
	s_waitcnt vmcnt(60) lgkmcnt(2)
	v_pk_fma_f32 v[4:5], v[132:133], v[148:149], v[4:5] op_sel_hi:[1,0,1]
	v_pk_fma_f32 v[2:3], v[132:133], v[152:153], v[2:3] op_sel_hi:[1,0,1]
	v_pk_fma_f32 v[4:5], v[134:135], v[148:149], v[4:5] op_sel:[0,1,0]
	v_pk_fma_f32 v[2:3], v[134:135], v[152:153], v[2:3] op_sel:[0,1,0]
	v_pk_fma_f32 v[4:5], v[136:137], v[150:151], v[4:5] op_sel_hi:[1,0,1]
	v_pk_fma_f32 v[2:3], v[136:137], v[154:155], v[2:3] op_sel_hi:[1,0,1]
	v_pk_fma_f32 v[4:5], v[138:139], v[150:151], v[4:5] op_sel:[0,1,0]
	v_pk_fma_f32 v[2:3], v[138:139], v[154:155], v[2:3] op_sel:[0,1,0]
	global_load_dwordx2 v[132:133], v158, s[8:9] nt
	s_add_u32 s8, s8, 0x6000
	s_addc_u32 s9, s9, 0
	global_load_dwordx2 v[134:135], v158, s[8:9] nt
	s_add_u32 s8, s8, 0x6000
	s_addc_u32 s9, s9, 0
	global_load_dwordx2 v[136:137], v158, s[8:9] nt
	s_add_u32 s8, s8, 0x6000
	s_addc_u32 s9, s9, 0
	global_load_dwordx2 v[138:139], v158, s[8:9] nt
	ds_read_b128 v[148:151], v1 offset:272
	ds_read_b128 v[152:155], v1 offset:4368
	s_waitcnt vmcnt(60) lgkmcnt(2)
	v_pk_fma_f32 v[4:5], v[6:7], v[140:141], v[4:5] op_sel_hi:[1,0,1]
	v_pk_fma_f32 v[2:3], v[6:7], v[144:145], v[2:3] op_sel_hi:[1,0,1]
	v_pk_fma_f32 v[4:5], v[8:9], v[140:141], v[4:5] op_sel:[0,1,0]
	v_pk_fma_f32 v[2:3], v[8:9], v[144:145], v[2:3] op_sel:[0,1,0]
	v_pk_fma_f32 v[4:5], v[10:11], v[142:143], v[4:5] op_sel_hi:[1,0,1]
	v_pk_fma_f32 v[2:3], v[10:11], v[146:147], v[2:3] op_sel_hi:[1,0,1]
	v_pk_fma_f32 v[4:5], v[12:13], v[142:143], v[4:5] op_sel:[0,1,0]
	v_pk_fma_f32 v[2:3], v[12:13], v[146:147], v[2:3] op_sel:[0,1,0]
	ds_read_b128 v[140:143], v1 offset:288
	ds_read_b128 v[144:147], v1 offset:4384
	s_waitcnt vmcnt(56) lgkmcnt(2)
	v_pk_fma_f32 v[4:5], v[14:15], v[148:149], v[4:5] op_sel_hi:[1,0,1]
	v_pk_fma_f32 v[2:3], v[14:15], v[152:153], v[2:3] op_sel_hi:[1,0,1]
	v_pk_fma_f32 v[4:5], v[16:17], v[148:149], v[4:5] op_sel:[0,1,0]
	v_pk_fma_f32 v[2:3], v[16:17], v[152:153], v[2:3] op_sel:[0,1,0]
	v_pk_fma_f32 v[4:5], v[18:19], v[150:151], v[4:5] op_sel_hi:[1,0,1]
	v_pk_fma_f32 v[2:3], v[18:19], v[154:155], v[2:3] op_sel_hi:[1,0,1]
	v_pk_fma_f32 v[4:5], v[20:21], v[150:151], v[4:5] op_sel:[0,1,0]
	v_pk_fma_f32 v[2:3], v[20:21], v[154:155], v[2:3] op_sel:[0,1,0]
	ds_read_b128 v[148:151], v1 offset:304
	ds_read_b128 v[152:155], v1 offset:4400
	s_waitcnt vmcnt(52) lgkmcnt(2)
	v_pk_fma_f32 v[4:5], v[22:23], v[140:141], v[4:5] op_sel_hi:[1,0,1]
	v_pk_fma_f32 v[2:3], v[22:23], v[144:145], v[2:3] op_sel_hi:[1,0,1]
	v_pk_fma_f32 v[4:5], v[24:25], v[140:141], v[4:5] op_sel:[0,1,0]
	v_pk_fma_f32 v[2:3], v[24:25], v[144:145], v[2:3] op_sel:[0,1,0]
	v_pk_fma_f32 v[4:5], v[26:27], v[142:143], v[4:5] op_sel_hi:[1,0,1]
	v_pk_fma_f32 v[2:3], v[26:27], v[146:147], v[2:3] op_sel_hi:[1,0,1]
	v_pk_fma_f32 v[4:5], v[28:29], v[142:143], v[4:5] op_sel:[0,1,0]
	v_pk_fma_f32 v[2:3], v[28:29], v[146:147], v[2:3] op_sel:[0,1,0]
	ds_read_b128 v[140:143], v1 offset:320
	ds_read_b128 v[144:147], v1 offset:4416
	s_waitcnt vmcnt(48) lgkmcnt(2)
	v_pk_fma_f32 v[4:5], v[30:31], v[148:149], v[4:5] op_sel_hi:[1,0,1]
	v_pk_fma_f32 v[2:3], v[30:31], v[152:153], v[2:3] op_sel_hi:[1,0,1]
	v_pk_fma_f32 v[4:5], v[32:33], v[148:149], v[4:5] op_sel:[0,1,0]
	v_pk_fma_f32 v[2:3], v[32:33], v[152:153], v[2:3] op_sel:[0,1,0]
	v_pk_fma_f32 v[4:5], v[34:35], v[150:151], v[4:5] op_sel_hi:[1,0,1]
	v_pk_fma_f32 v[2:3], v[34:35], v[154:155], v[2:3] op_sel_hi:[1,0,1]
	v_pk_fma_f32 v[4:5], v[36:37], v[150:151], v[4:5] op_sel:[0,1,0]
	v_pk_fma_f32 v[2:3], v[36:37], v[154:155], v[2:3] op_sel:[0,1,0]
	ds_read_b128 v[148:151], v1 offset:336
	ds_read_b128 v[152:155], v1 offset:4432
	s_waitcnt vmcnt(44) lgkmcnt(2)
	v_pk_fma_f32 v[4:5], v[38:39], v[140:141], v[4:5] op_sel_hi:[1,0,1]
	v_pk_fma_f32 v[2:3], v[38:39], v[144:145], v[2:3] op_sel_hi:[1,0,1]
	v_pk_fma_f32 v[4:5], v[40:41], v[140:141], v[4:5] op_sel:[0,1,0]
	v_pk_fma_f32 v[2:3], v[40:41], v[144:145], v[2:3] op_sel:[0,1,0]
	v_pk_fma_f32 v[4:5], v[42:43], v[142:143], v[4:5] op_sel_hi:[1,0,1]
	v_pk_fma_f32 v[2:3], v[42:43], v[146:147], v[2:3] op_sel_hi:[1,0,1]
	v_pk_fma_f32 v[4:5], v[44:45], v[142:143], v[4:5] op_sel:[0,1,0]
	v_pk_fma_f32 v[2:3], v[44:45], v[146:147], v[2:3] op_sel:[0,1,0]
	ds_read_b128 v[140:143], v1 offset:352
	ds_read_b128 v[144:147], v1 offset:4448
	s_waitcnt vmcnt(40) lgkmcnt(2)
	v_pk_fma_f32 v[4:5], v[46:47], v[148:149], v[4:5] op_sel_hi:[1,0,1]
	v_pk_fma_f32 v[2:3], v[46:47], v[152:153], v[2:3] op_sel_hi:[1,0,1]
	v_pk_fma_f32 v[4:5], v[48:49], v[148:149], v[4:5] op_sel:[0,1,0]
	v_pk_fma_f32 v[2:3], v[48:49], v[152:153], v[2:3] op_sel:[0,1,0]
	v_pk_fma_f32 v[4:5], v[50:51], v[150:151], v[4:5] op_sel_hi:[1,0,1]
	v_pk_fma_f32 v[2:3], v[50:51], v[154:155], v[2:3] op_sel_hi:[1,0,1]
	v_pk_fma_f32 v[4:5], v[52:53], v[150:151], v[4:5] op_sel:[0,1,0]
	v_pk_fma_f32 v[2:3], v[52:53], v[154:155], v[2:3] op_sel:[0,1,0]
	ds_read_b128 v[148:151], v1 offset:368
	ds_read_b128 v[152:155], v1 offset:4464
	s_waitcnt vmcnt(36) lgkmcnt(2)
	v_pk_fma_f32 v[4:5], v[54:55], v[140:141], v[4:5] op_sel_hi:[1,0,1]
	v_pk_fma_f32 v[2:3], v[54:55], v[144:145], v[2:3] op_sel_hi:[1,0,1]
	v_pk_fma_f32 v[4:5], v[56:57], v[140:141], v[4:5] op_sel:[0,1,0]
	v_pk_fma_f32 v[2:3], v[56:57], v[144:145], v[2:3] op_sel:[0,1,0]
	v_pk_fma_f32 v[4:5], v[58:59], v[142:143], v[4:5] op_sel_hi:[1,0,1]
	v_pk_fma_f32 v[2:3], v[58:59], v[146:147], v[2:3] op_sel_hi:[1,0,1]
	v_pk_fma_f32 v[4:5], v[60:61], v[142:143], v[4:5] op_sel:[0,1,0]
	v_pk_fma_f32 v[2:3], v[60:61], v[146:147], v[2:3] op_sel:[0,1,0]
	ds_read_b128 v[140:143], v1 offset:384
	ds_read_b128 v[144:147], v1 offset:4480
	s_waitcnt vmcnt(32) lgkmcnt(2)
	v_pk_fma_f32 v[4:5], v[62:63], v[148:149], v[4:5] op_sel_hi:[1,0,1]
	v_pk_fma_f32 v[2:3], v[62:63], v[152:153], v[2:3] op_sel_hi:[1,0,1]
	v_pk_fma_f32 v[4:5], v[64:65], v[148:149], v[4:5] op_sel:[0,1,0]
	v_pk_fma_f32 v[2:3], v[64:65], v[152:153], v[2:3] op_sel:[0,1,0]
	v_pk_fma_f32 v[4:5], v[66:67], v[150:151], v[4:5] op_sel_hi:[1,0,1]
	v_pk_fma_f32 v[2:3], v[66:67], v[154:155], v[2:3] op_sel_hi:[1,0,1]
	v_pk_fma_f32 v[4:5], v[68:69], v[150:151], v[4:5] op_sel:[0,1,0]
	v_pk_fma_f32 v[2:3], v[68:69], v[154:155], v[2:3] op_sel:[0,1,0]
	ds_read_b128 v[148:151], v1 offset:400
	ds_read_b128 v[152:155], v1 offset:4496
	s_waitcnt vmcnt(28) lgkmcnt(2)
	v_pk_fma_f32 v[4:5], v[70:71], v[140:141], v[4:5] op_sel_hi:[1,0,1]
	v_pk_fma_f32 v[2:3], v[70:71], v[144:145], v[2:3] op_sel_hi:[1,0,1]
	v_pk_fma_f32 v[4:5], v[72:73], v[140:141], v[4:5] op_sel:[0,1,0]
	v_pk_fma_f32 v[2:3], v[72:73], v[144:145], v[2:3] op_sel:[0,1,0]
	v_pk_fma_f32 v[4:5], v[80:81], v[142:143], v[4:5] op_sel_hi:[1,0,1]
	v_pk_fma_f32 v[2:3], v[80:81], v[146:147], v[2:3] op_sel_hi:[1,0,1]
	v_pk_fma_f32 v[4:5], v[82:83], v[142:143], v[4:5] op_sel:[0,1,0]
	v_pk_fma_f32 v[2:3], v[82:83], v[146:147], v[2:3] op_sel:[0,1,0]
	ds_read_b128 v[140:143], v1 offset:416
	ds_read_b128 v[144:147], v1 offset:4512
	s_waitcnt vmcnt(24) lgkmcnt(2)
	v_pk_fma_f32 v[4:5], v[84:85], v[148:149], v[4:5] op_sel_hi:[1,0,1]
	v_pk_fma_f32 v[2:3], v[84:85], v[152:153], v[2:3] op_sel_hi:[1,0,1]
	v_pk_fma_f32 v[4:5], v[86:87], v[148:149], v[4:5] op_sel:[0,1,0]
	v_pk_fma_f32 v[2:3], v[86:87], v[152:153], v[2:3] op_sel:[0,1,0]
	v_pk_fma_f32 v[4:5], v[88:89], v[150:151], v[4:5] op_sel_hi:[1,0,1]
	v_pk_fma_f32 v[2:3], v[88:89], v[154:155], v[2:3] op_sel_hi:[1,0,1]
	v_pk_fma_f32 v[4:5], v[90:91], v[150:151], v[4:5] op_sel:[0,1,0]
	v_pk_fma_f32 v[2:3], v[90:91], v[154:155], v[2:3] op_sel:[0,1,0]
	ds_read_b128 v[148:151], v1 offset:432
	ds_read_b128 v[152:155], v1 offset:4528
	s_waitcnt vmcnt(20) lgkmcnt(2)
	v_pk_fma_f32 v[4:5], v[92:93], v[140:141], v[4:5] op_sel_hi:[1,0,1]
	v_pk_fma_f32 v[2:3], v[92:93], v[144:145], v[2:3] op_sel_hi:[1,0,1]
	v_pk_fma_f32 v[4:5], v[94:95], v[140:141], v[4:5] op_sel:[0,1,0]
	v_pk_fma_f32 v[2:3], v[94:95], v[144:145], v[2:3] op_sel:[0,1,0]
	v_pk_fma_f32 v[4:5], v[96:97], v[142:143], v[4:5] op_sel_hi:[1,0,1]
	v_pk_fma_f32 v[2:3], v[96:97], v[146:147], v[2:3] op_sel_hi:[1,0,1]
	v_pk_fma_f32 v[4:5], v[98:99], v[142:143], v[4:5] op_sel:[0,1,0]
	v_pk_fma_f32 v[2:3], v[98:99], v[146:147], v[2:3] op_sel:[0,1,0]
	ds_read_b128 v[140:143], v1 offset:448
	ds_read_b128 v[144:147], v1 offset:4544
	s_waitcnt vmcnt(16) lgkmcnt(2)
	v_pk_fma_f32 v[4:5], v[100:101], v[148:149], v[4:5] op_sel_hi:[1,0,1]
	v_pk_fma_f32 v[2:3], v[100:101], v[152:153], v[2:3] op_sel_hi:[1,0,1]
	v_pk_fma_f32 v[4:5], v[102:103], v[148:149], v[4:5] op_sel:[0,1,0]
	v_pk_fma_f32 v[2:3], v[102:103], v[152:153], v[2:3] op_sel:[0,1,0]
	v_pk_fma_f32 v[4:5], v[104:105], v[150:151], v[4:5] op_sel_hi:[1,0,1]
	v_pk_fma_f32 v[2:3], v[104:105], v[154:155], v[2:3] op_sel_hi:[1,0,1]
	v_pk_fma_f32 v[4:5], v[106:107], v[150:151], v[4:5] op_sel:[0,1,0]
	v_pk_fma_f32 v[2:3], v[106:107], v[154:155], v[2:3] op_sel:[0,1,0]
	ds_read_b128 v[148:151], v1 offset:464
	ds_read_b128 v[152:155], v1 offset:4560
	s_waitcnt vmcnt(12) lgkmcnt(2)
	v_pk_fma_f32 v[4:5], v[108:109], v[140:141], v[4:5] op_sel_hi:[1,0,1]
	v_pk_fma_f32 v[2:3], v[108:109], v[144:145], v[2:3] op_sel_hi:[1,0,1]
	v_pk_fma_f32 v[4:5], v[110:111], v[140:141], v[4:5] op_sel:[0,1,0]
	v_pk_fma_f32 v[2:3], v[110:111], v[144:145], v[2:3] op_sel:[0,1,0]
	v_pk_fma_f32 v[4:5], v[112:113], v[142:143], v[4:5] op_sel_hi:[1,0,1]
	v_pk_fma_f32 v[2:3], v[112:113], v[146:147], v[2:3] op_sel_hi:[1,0,1]
	v_pk_fma_f32 v[4:5], v[114:115], v[142:143], v[4:5] op_sel:[0,1,0]
	v_pk_fma_f32 v[2:3], v[114:115], v[146:147], v[2:3] op_sel:[0,1,0]
	ds_read_b128 v[140:143], v1 offset:480
	ds_read_b128 v[144:147], v1 offset:4576
	s_waitcnt vmcnt(8) lgkmcnt(2)
	v_pk_fma_f32 v[4:5], v[116:117], v[148:149], v[4:5] op_sel_hi:[1,0,1]
	v_pk_fma_f32 v[2:3], v[116:117], v[152:153], v[2:3] op_sel_hi:[1,0,1]
	v_pk_fma_f32 v[4:5], v[118:119], v[148:149], v[4:5] op_sel:[0,1,0]
	v_pk_fma_f32 v[2:3], v[118:119], v[152:153], v[2:3] op_sel:[0,1,0]
	v_pk_fma_f32 v[4:5], v[120:121], v[150:151], v[4:5] op_sel_hi:[1,0,1]
	v_pk_fma_f32 v[2:3], v[120:121], v[154:155], v[2:3] op_sel_hi:[1,0,1]
	v_pk_fma_f32 v[4:5], v[122:123], v[150:151], v[4:5] op_sel:[0,1,0]
	v_pk_fma_f32 v[2:3], v[122:123], v[154:155], v[2:3] op_sel:[0,1,0]
	ds_read_b128 v[148:151], v1 offset:496
	ds_read_b128 v[152:155], v1 offset:4592
	s_waitcnt vmcnt(4) lgkmcnt(2)
	v_pk_fma_f32 v[4:5], v[124:125], v[140:141], v[4:5] op_sel_hi:[1,0,1]
	v_pk_fma_f32 v[2:3], v[124:125], v[144:145], v[2:3] op_sel_hi:[1,0,1]
	v_pk_fma_f32 v[4:5], v[126:127], v[140:141], v[4:5] op_sel:[0,1,0]
	v_pk_fma_f32 v[2:3], v[126:127], v[144:145], v[2:3] op_sel:[0,1,0]
	v_pk_fma_f32 v[4:5], v[128:129], v[142:143], v[4:5] op_sel_hi:[1,0,1]
	v_pk_fma_f32 v[2:3], v[128:129], v[146:147], v[2:3] op_sel_hi:[1,0,1]
	v_pk_fma_f32 v[4:5], v[130:131], v[142:143], v[4:5] op_sel:[0,1,0]
	v_pk_fma_f32 v[2:3], v[130:131], v[146:147], v[2:3] op_sel:[0,1,0]
	s_waitcnt vmcnt(0) lgkmcnt(0)
	v_pk_fma_f32 v[4:5], v[132:133], v[148:149], v[4:5] op_sel_hi:[1,0,1]
	v_pk_fma_f32 v[2:3], v[132:133], v[152:153], v[2:3] op_sel_hi:[1,0,1]
	v_pk_fma_f32 v[4:5], v[134:135], v[148:149], v[4:5] op_sel:[0,1,0]
	v_pk_fma_f32 v[2:3], v[134:135], v[152:153], v[2:3] op_sel:[0,1,0]
	v_pk_fma_f32 v[4:5], v[136:137], v[150:151], v[4:5] op_sel_hi:[1,0,1]
	v_pk_fma_f32 v[2:3], v[136:137], v[154:155], v[2:3] op_sel_hi:[1,0,1]
	v_pk_fma_f32 v[4:5], v[138:139], v[150:151], v[4:5] op_sel:[0,1,0]
	v_pk_fma_f32 v[2:3], v[138:139], v[154:155], v[2:3] op_sel:[0,1,0]
	s_lshl_b32 s4, s90, 2
	s_lshl_b32 s5, s87, 1
	s_add_i32 s8, s4, s5
	s_mul_i32 s5, s8, 0x6000
	s_mul_hi_i32 s4, s8, 0x6000
	s_add_u32 s5, s45, s5
	s_addc_u32 s9, s46, s4
	s_add_u32 s4, s5, s40
	s_addc_u32 s5, s9, s41
	global_store_dwordx2 v158, v[4:5], s[4:5]
	s_or_b32 s4, s8, 1
	s_mul_hi_i32 s5, s4, 0x6000
	s_mulk_i32 s4, 0x6000
	s_add_u32 s4, s45, s4
	s_addc_u32 s5, s46, s5
	s_add_u32 s4, s4, s40
	s_addc_u32 s5, s5, s41
	s_add_i32 s7, s7, s3
	s_cmpk_gt_i32 s7, 0x2ff
	global_store_dwordx2 v158, v[2:3], s[4:5]
	s_cbranch_scc0 .LBB0_14
